# residual GEMM epilogues rewritten: second-half residual loads issued before the first-half stores (overlap load round trip with store drain), progressive waits
# speedup vs baseline: 1.0153x; 1.0153x over previous
.LBB0_133:
	s_add_u32 s28, s22, 0x100
	s_addc_u32 s29, s23, 0
	s_add_i32 s85, 0, 0x10000
	v_add_u32_e32 v148, s85, v157
	ds_read_b128 v[130:133], v148
	ds_read_b128 v[134:137], v148 offset:1024
	ds_read_b128 v[138:141], v148 offset:2048
	ds_read_b128 v[148:151], v148 offset:3072
	s_cmp_eq_u32 s84, 40
	s_cselect_b32 s43, s17, s29
	s_cselect_b32 s42, s16, s28
	s_cselect_b32 s41, s19, s79
	s_cselect_b32 s40, s18, s34
	v_lshl_add_u64 v[188:189], s[22:23], 0, v[146:147]
	s_add_i32 m0, s54, 0xc000
	ds_read_b128 v[152:155], v159
	ds_read_b128 v[160:163], v159 offset:1024
	ds_read_b128 v[164:167], v159 offset:2048
	ds_read_b128 v[168:171], v159 offset:3072
	ds_read_b128 v[172:175], v159 offset:4096
	ds_read_b128 v[176:179], v159 offset:5120
	ds_read_b128 v[180:183], v159 offset:6144
	ds_read_b128 v[184:187], v159 offset:7168
	global_load_lds_dwordx4 v[188:189], off
	v_lshl_add_u64 v[188:189], s[22:23], 0, v[144:145]
	s_add_i32 m0, s54, 0xe000
	s_nop 0
	global_load_lds_dwordx4 v[188:189], off
	s_waitcnt lgkmcnt(8)
	s_barrier
	s_waitcnt lgkmcnt(0)
	s_waitcnt lgkmcnt(0)
	v_mfma_f32_16x16x32_bf16 v[126:129], v[130:133], v[152:155], v[126:129]
	v_mfma_f32_16x16x32_bf16 v[122:125], v[138:141], v[152:155], v[122:125]
	v_mfma_f32_16x16x32_bf16 v[118:121], v[130:133], v[164:167], v[118:121]
	v_mfma_f32_16x16x32_bf16 v[106:109], v[138:141], v[164:167], v[106:109]
	v_mfma_f32_16x16x32_bf16 v[102:105], v[130:133], v[172:175], v[102:105]
	v_mfma_f32_16x16x32_bf16 v[90:93], v[138:141], v[172:175], v[90:93]
	v_mfma_f32_16x16x32_bf16 v[86:89], v[130:133], v[180:183], v[86:89]
	v_mfma_f32_16x16x32_bf16 v[74:77], v[138:141], v[180:183], v[74:77]
	v_mfma_f32_16x16x32_bf16 v[126:129], v[134:137], v[160:163], v[126:129]
	v_mfma_f32_16x16x32_bf16 v[122:125], v[148:151], v[160:163], v[122:125]
	v_mfma_f32_16x16x32_bf16 v[118:121], v[134:137], v[168:171], v[118:121]
	v_mfma_f32_16x16x32_bf16 v[106:109], v[148:151], v[168:171], v[106:109]
	v_mfma_f32_16x16x32_bf16 v[102:105], v[134:137], v[176:179], v[102:105]
	v_mfma_f32_16x16x32_bf16 v[90:93], v[148:151], v[176:179], v[90:93]
	v_mfma_f32_16x16x32_bf16 v[86:89], v[134:137], v[184:187], v[86:89]
	v_mfma_f32_16x16x32_bf16 v[74:77], v[148:151], v[184:187], v[74:77]
	s_barrier
	s_add_i32 s86, 0, 0x14000
	v_add_u32_e32 v196, s86, v157
	s_add_i32 s22, s85, s50
	ds_read_b128 v[188:191], v196
	ds_read_b128 v[192:195], v196 offset:1024
	ds_read_b128 v[208:211], v196 offset:2048
	ds_read_b128 v[212:215], v196 offset:3072
	v_lshl_add_u64 v[196:197], s[40:41], 0, v[16:17]
	s_mov_b32 m0, s22
	v_lshl_add_u64 v[216:217], s[40:41], 0, v[142:143]
	global_load_lds_dwordx4 v[196:197], off
	s_add_i32 m0, s22, 0x2000
	s_nop 0
	global_load_lds_dwordx4 v[216:217], off
	s_barrier
	s_waitcnt lgkmcnt(0)
	s_waitcnt lgkmcnt(0)
	v_mfma_f32_16x16x32_bf16 v[114:117], v[188:191], v[152:155], v[114:117]
	v_mfma_f32_16x16x32_bf16 v[110:113], v[208:211], v[152:155], v[110:113]
	v_mfma_f32_16x16x32_bf16 v[98:101], v[188:191], v[164:167], v[98:101]
	v_mfma_f32_16x16x32_bf16 v[94:97], v[208:211], v[164:167], v[94:97]
	v_mfma_f32_16x16x32_bf16 v[82:85], v[188:191], v[172:175], v[82:85]
	v_mfma_f32_16x16x32_bf16 v[78:81], v[208:211], v[172:175], v[78:81]
	v_mfma_f32_16x16x32_bf16 v[70:73], v[188:191], v[180:183], v[70:73]
	v_mfma_f32_16x16x32_bf16 v[66:69], v[208:211], v[180:183], v[66:69]
	v_mfma_f32_16x16x32_bf16 v[114:117], v[192:195], v[160:163], v[114:117]
	v_mfma_f32_16x16x32_bf16 v[110:113], v[212:215], v[160:163], v[110:113]
	v_mfma_f32_16x16x32_bf16 v[98:101], v[192:195], v[168:171], v[98:101]
	v_mfma_f32_16x16x32_bf16 v[94:97], v[212:215], v[168:171], v[94:97]
	v_mfma_f32_16x16x32_bf16 v[82:85], v[192:195], v[176:179], v[82:85]
	v_mfma_f32_16x16x32_bf16 v[78:81], v[212:215], v[176:179], v[78:81]
	v_mfma_f32_16x16x32_bf16 v[70:73], v[192:195], v[184:187], v[70:73]
	v_mfma_f32_16x16x32_bf16 v[66:69], v[212:215], v[184:187], v[66:69]
	s_mov_b32 m0, s54
	v_lshl_add_u64 v[218:219], s[42:43], 0, v[16:17]
	s_barrier
	ds_read_b128 v[152:155], v159 offset:16384
	ds_read_b128 v[160:163], v159 offset:17408
	ds_read_b128 v[164:167], v159 offset:18432
	ds_read_b128 v[168:171], v159 offset:19456
	ds_read_b128 v[172:175], v159 offset:20480
	ds_read_b128 v[176:179], v159 offset:21504
	ds_read_b128 v[180:183], v159 offset:22528
	ds_read_b128 v[184:187], v159 offset:23552
	global_load_lds_dwordx4 v[218:219], off
	v_lshl_add_u64 v[220:221], s[42:43], 0, v[142:143]
	s_mov_b32 m0, s55
	s_nop 0
	global_load_lds_dwordx4 v[220:221], off
	s_barrier
	s_waitcnt lgkmcnt(0)
	s_waitcnt lgkmcnt(0)
	v_mfma_f32_16x16x32_bf16 v[62:65], v[130:133], v[152:155], v[62:65]
	v_mfma_f32_16x16x32_bf16 v[58:61], v[138:141], v[152:155], v[58:61]
	v_mfma_f32_16x16x32_bf16 v[54:57], v[130:133], v[164:167], v[54:57]
	v_mfma_f32_16x16x32_bf16 v[50:53], v[138:141], v[164:167], v[50:53]
	v_mfma_f32_16x16x32_bf16 v[46:49], v[130:133], v[172:175], v[46:49]
	v_mfma_f32_16x16x32_bf16 v[38:41], v[138:141], v[172:175], v[38:41]
	v_mfma_f32_16x16x32_bf16 v[30:33], v[130:133], v[180:183], v[30:33]
	v_mfma_f32_16x16x32_bf16 v[18:21], v[138:141], v[180:183], v[18:21]
	v_mfma_f32_16x16x32_bf16 v[62:65], v[134:137], v[160:163], v[62:65]
	v_mfma_f32_16x16x32_bf16 v[58:61], v[148:151], v[160:163], v[58:61]
	v_mfma_f32_16x16x32_bf16 v[54:57], v[134:137], v[168:171], v[54:57]
	v_mfma_f32_16x16x32_bf16 v[50:53], v[148:151], v[168:171], v[50:53]
	v_mfma_f32_16x16x32_bf16 v[46:49], v[134:137], v[176:179], v[46:49]
	v_mfma_f32_16x16x32_bf16 v[38:41], v[148:151], v[176:179], v[38:41]
	v_mfma_f32_16x16x32_bf16 v[30:33], v[134:137], v[184:187], v[30:33]
	v_mfma_f32_16x16x32_bf16 v[18:21], v[148:151], v[184:187], v[18:21]
	s_barrier
	s_add_u32 s22, s40, 0xb0000
	s_addc_u32 s23, s41, 0
	s_add_i32 s85, s86, s50
	v_lshl_add_u64 v[130:131], s[22:23], 0, v[16:17]
	s_mov_b32 m0, s85
	s_nop 0
	global_load_lds_dwordx4 v[130:131], off
	v_lshl_add_u64 v[130:131], s[22:23], 0, v[142:143]
	s_add_i32 m0, s85, 0x2000
	s_nop 0
	global_load_lds_dwordx4 v[130:131], off
	s_waitcnt vmcnt(6)
	s_barrier
	v_mfma_f32_16x16x32_bf16 v[42:45], v[188:191], v[152:155], v[42:45]
	v_mfma_f32_16x16x32_bf16 v[34:37], v[208:211], v[152:155], v[34:37]
	v_mfma_f32_16x16x32_bf16 v[26:29], v[188:191], v[164:167], v[26:29]
	v_mfma_f32_16x16x32_bf16 v[22:25], v[208:211], v[164:167], v[22:25]
	v_mfma_f32_16x16x32_bf16 v[12:15], v[188:191], v[172:175], v[12:15]
	v_mfma_f32_16x16x32_bf16 v[8:11], v[208:211], v[172:175], v[8:11]
	v_mfma_f32_16x16x32_bf16 v[4:7], v[188:191], v[180:183], v[4:7]
	v_mfma_f32_16x16x32_bf16 v[0:3], v[208:211], v[180:183], v[0:3]
	v_mfma_f32_16x16x32_bf16 v[42:45], v[192:195], v[160:163], v[42:45]
	v_mfma_f32_16x16x32_bf16 v[34:37], v[212:215], v[160:163], v[34:37]
	v_mfma_f32_16x16x32_bf16 v[26:29], v[192:195], v[168:171], v[26:29]
	v_mfma_f32_16x16x32_bf16 v[22:25], v[212:215], v[168:171], v[22:25]
	v_mfma_f32_16x16x32_bf16 v[12:15], v[192:195], v[176:179], v[12:15]
	v_mfma_f32_16x16x32_bf16 v[8:11], v[212:215], v[176:179], v[8:11]
	v_mfma_f32_16x16x32_bf16 v[4:7], v[192:195], v[184:187], v[4:7]
	v_mfma_f32_16x16x32_bf16 v[0:3], v[212:215], v[184:187], v[0:3]
	s_add_i32 s85, 0, 0x18000
	v_add_u32_e32 v148, s85, v157
	s_barrier
	ds_read_b128 v[130:133], v148
	ds_read_b128 v[134:137], v148 offset:1024
	ds_read_b128 v[138:141], v148 offset:2048
	ds_read_b128 v[148:151], v148 offset:3072
	s_add_u32 s22, s42, 0xb0000
	s_addc_u32 s23, s43, 0
	s_mov_b32 m0, s56
	v_lshl_add_u64 v[188:189], s[22:23], 0, v[16:17]
	ds_read_b128 v[152:155], v159 offset:32768
	ds_read_b128 v[160:163], v159 offset:33792
	ds_read_b128 v[164:167], v159 offset:34816
	ds_read_b128 v[168:171], v159 offset:35840
	ds_read_b128 v[172:175], v159 offset:36864
	ds_read_b128 v[176:179], v159 offset:37888
	ds_read_b128 v[180:183], v159 offset:38912
	ds_read_b128 v[184:187], v159 offset:39936
	global_load_lds_dwordx4 v[188:189], off
	v_lshl_add_u64 v[188:189], s[22:23], 0, v[142:143]
	s_mov_b32 m0, s57
	s_nop 0
	global_load_lds_dwordx4 v[188:189], off
	s_waitcnt lgkmcnt(8)
	s_barrier
	s_waitcnt lgkmcnt(0)
	s_waitcnt lgkmcnt(0)
	v_mfma_f32_16x16x32_bf16 v[126:129], v[130:133], v[152:155], v[126:129]
	v_mfma_f32_16x16x32_bf16 v[122:125], v[138:141], v[152:155], v[122:125]
	v_mfma_f32_16x16x32_bf16 v[118:121], v[130:133], v[164:167], v[118:121]
	v_mfma_f32_16x16x32_bf16 v[106:109], v[138:141], v[164:167], v[106:109]
	v_mfma_f32_16x16x32_bf16 v[102:105], v[130:133], v[172:175], v[102:105]
	v_mfma_f32_16x16x32_bf16 v[90:93], v[138:141], v[172:175], v[90:93]
	v_mfma_f32_16x16x32_bf16 v[86:89], v[130:133], v[180:183], v[86:89]
	v_mfma_f32_16x16x32_bf16 v[74:77], v[138:141], v[180:183], v[74:77]
	v_mfma_f32_16x16x32_bf16 v[126:129], v[134:137], v[160:163], v[126:129]
	v_mfma_f32_16x16x32_bf16 v[122:125], v[148:151], v[160:163], v[122:125]
	v_mfma_f32_16x16x32_bf16 v[118:121], v[134:137], v[168:171], v[118:121]
	v_mfma_f32_16x16x32_bf16 v[106:109], v[148:151], v[168:171], v[106:109]
	v_mfma_f32_16x16x32_bf16 v[102:105], v[134:137], v[176:179], v[102:105]
	v_mfma_f32_16x16x32_bf16 v[90:93], v[148:151], v[176:179], v[90:93]
	v_mfma_f32_16x16x32_bf16 v[86:89], v[134:137], v[184:187], v[86:89]
	v_mfma_f32_16x16x32_bf16 v[74:77], v[148:151], v[184:187], v[74:77]
	s_barrier
	s_add_i32 s42, 0, 0x1c000
	s_add_i32 s22, s85, s50
	v_add_u32_e32 v212, s42, v157
	v_lshl_add_u64 v[196:197], v[196:197], 0, s[10:11]
	s_mov_b32 m0, s22
	ds_read_b128 v[188:191], v212
	ds_read_b128 v[192:195], v212 offset:1024
	ds_read_b128 v[208:211], v212 offset:2048
	ds_read_b128 v[212:215], v212 offset:3072
	global_load_lds_dwordx4 v[196:197], off
	v_lshl_add_u64 v[196:197], v[216:217], 0, s[10:11]
	s_add_i32 m0, s22, 0x2000
	s_nop 0
	global_load_lds_dwordx4 v[196:197], off
	s_barrier
	s_waitcnt lgkmcnt(0)
	s_waitcnt lgkmcnt(0)
	v_mfma_f32_16x16x32_bf16 v[114:117], v[188:191], v[152:155], v[114:117]
	v_mfma_f32_16x16x32_bf16 v[110:113], v[208:211], v[152:155], v[110:113]
	v_mfma_f32_16x16x32_bf16 v[98:101], v[188:191], v[164:167], v[98:101]
	v_mfma_f32_16x16x32_bf16 v[94:97], v[208:211], v[164:167], v[94:97]
	v_mfma_f32_16x16x32_bf16 v[82:85], v[188:191], v[172:175], v[82:85]
	v_mfma_f32_16x16x32_bf16 v[78:81], v[208:211], v[172:175], v[78:81]
	v_mfma_f32_16x16x32_bf16 v[70:73], v[188:191], v[180:183], v[70:73]
	v_mfma_f32_16x16x32_bf16 v[66:69], v[208:211], v[180:183], v[66:69]
	v_mfma_f32_16x16x32_bf16 v[114:117], v[192:195], v[160:163], v[114:117]
	v_mfma_f32_16x16x32_bf16 v[110:113], v[212:215], v[160:163], v[110:113]
	v_mfma_f32_16x16x32_bf16 v[98:101], v[192:195], v[168:171], v[98:101]
	v_mfma_f32_16x16x32_bf16 v[94:97], v[212:215], v[168:171], v[94:97]
	v_mfma_f32_16x16x32_bf16 v[82:85], v[192:195], v[176:179], v[82:85]
	v_mfma_f32_16x16x32_bf16 v[78:81], v[212:215], v[176:179], v[78:81]
	v_mfma_f32_16x16x32_bf16 v[70:73], v[192:195], v[184:187], v[70:73]
	v_mfma_f32_16x16x32_bf16 v[66:69], v[212:215], v[184:187], v[66:69]
	s_mov_b32 m0, s58
	v_lshl_add_u64 v[196:197], v[218:219], 0, s[10:11]
	s_barrier
	ds_read_b128 v[152:155], v159 offset:49152
	ds_read_b128 v[160:163], v159 offset:50176
	ds_read_b128 v[164:167], v159 offset:51200
	ds_read_b128 v[168:171], v159 offset:52224
	ds_read_b128 v[172:175], v159 offset:53248
	ds_read_b128 v[176:179], v159 offset:54272
	ds_read_b128 v[180:183], v159 offset:55296
	ds_read_b128 v[184:187], v159 offset:56320
	global_load_lds_dwordx4 v[196:197], off
	v_lshl_add_u64 v[196:197], v[220:221], 0, s[10:11]
	s_mov_b32 m0, s59
	s_nop 0
	global_load_lds_dwordx4 v[196:197], off
	s_barrier
	s_waitcnt lgkmcnt(0)
	s_waitcnt lgkmcnt(0)
	v_mfma_f32_16x16x32_bf16 v[62:65], v[130:133], v[152:155], v[62:65]
	v_mfma_f32_16x16x32_bf16 v[58:61], v[138:141], v[152:155], v[58:61]
	v_mfma_f32_16x16x32_bf16 v[54:57], v[130:133], v[164:167], v[54:57]
	v_mfma_f32_16x16x32_bf16 v[50:53], v[138:141], v[164:167], v[50:53]
	v_mfma_f32_16x16x32_bf16 v[46:49], v[130:133], v[172:175], v[46:49]
	v_mfma_f32_16x16x32_bf16 v[38:41], v[138:141], v[172:175], v[38:41]
	v_mfma_f32_16x16x32_bf16 v[30:33], v[130:133], v[180:183], v[30:33]
	v_mfma_f32_16x16x32_bf16 v[18:21], v[138:141], v[180:183], v[18:21]
	v_mfma_f32_16x16x32_bf16 v[62:65], v[134:137], v[160:163], v[62:65]
	v_mfma_f32_16x16x32_bf16 v[58:61], v[148:151], v[160:163], v[58:61]
	v_mfma_f32_16x16x32_bf16 v[54:57], v[134:137], v[168:171], v[54:57]
	v_mfma_f32_16x16x32_bf16 v[50:53], v[148:151], v[168:171], v[50:53]
	v_mfma_f32_16x16x32_bf16 v[46:49], v[134:137], v[176:179], v[46:49]
	v_mfma_f32_16x16x32_bf16 v[38:41], v[148:151], v[176:179], v[38:41]
	v_mfma_f32_16x16x32_bf16 v[30:33], v[134:137], v[184:187], v[30:33]
	v_mfma_f32_16x16x32_bf16 v[18:21], v[148:151], v[184:187], v[18:21]
	s_barrier
	s_add_u32 s22, s40, 0xb0080
	s_addc_u32 s23, s41, 0
	s_add_i32 s40, s42, s50
	v_lshl_add_u64 v[130:131], s[22:23], 0, v[16:17]
	s_mov_b32 m0, s40
	s_nop 0
	global_load_lds_dwordx4 v[130:131], off
	v_lshl_add_u64 v[130:131], s[22:23], 0, v[142:143]
	s_add_i32 m0, s40, 0x2000
	s_nop 0
	global_load_lds_dwordx4 v[130:131], off
	s_waitcnt vmcnt(6)
	s_barrier
	v_mfma_f32_16x16x32_bf16 v[42:45], v[188:191], v[152:155], v[42:45]
	v_mfma_f32_16x16x32_bf16 v[34:37], v[208:211], v[152:155], v[34:37]
	v_mfma_f32_16x16x32_bf16 v[26:29], v[188:191], v[164:167], v[26:29]
	v_mfma_f32_16x16x32_bf16 v[22:25], v[208:211], v[164:167], v[22:25]
	v_mfma_f32_16x16x32_bf16 v[12:15], v[188:191], v[172:175], v[12:15]
	v_mfma_f32_16x16x32_bf16 v[8:11], v[208:211], v[172:175], v[8:11]
	v_mfma_f32_16x16x32_bf16 v[4:7], v[188:191], v[180:183], v[4:7]
	v_mfma_f32_16x16x32_bf16 v[0:3], v[208:211], v[180:183], v[0:3]
	v_mfma_f32_16x16x32_bf16 v[42:45], v[192:195], v[160:163], v[42:45]
	v_mfma_f32_16x16x32_bf16 v[34:37], v[212:215], v[160:163], v[34:37]
	v_mfma_f32_16x16x32_bf16 v[26:29], v[192:195], v[168:171], v[26:29]
	v_mfma_f32_16x16x32_bf16 v[22:25], v[212:215], v[168:171], v[22:25]
	v_mfma_f32_16x16x32_bf16 v[12:15], v[192:195], v[176:179], v[12:15]
	v_mfma_f32_16x16x32_bf16 v[8:11], v[212:215], v[176:179], v[8:11]
	v_mfma_f32_16x16x32_bf16 v[4:7], v[192:195], v[184:187], v[4:7]
	v_mfma_f32_16x16x32_bf16 v[0:3], v[212:215], v[184:187], v[0:3]
	s_add_i32 s84, s84, 2
	s_add_u32 s34, s34, 0x100
	s_addc_u32 s79, s79, 0
	s_cmp_gt_u32 s84, 41
	s_mov_b64 s[22:23], s[28:29]
	s_barrier
	s_cbranch_scc0 .LBB0_133
	v_lshl_or_b32 v132, s12, 8, v158
	v_lshl_add_u32 v130, s2, 8, v156
	v_ashrrev_i32_e32 v133, 31, v132
	v_lshlrev_b64 v[148:149], 2, v[132:133]
	v_ashrrev_i32_e32 v131, 31, v130
	v_lshlrev_b64 v[152:153], 12, v[130:131]
	v_lshl_add_u64 v[150:151], s[4:5], 0, v[148:149]
	v_lshl_add_u64 v[154:155], v[150:151], 0, v[152:153]
	s_mov_b64 s[22:23], 0x10000
	v_lshl_add_u64 v[196:197], v[154:155], 0, s[22:23]
	s_mov_b64 s[22:23], 0x20000
	v_lshl_add_u64 v[224:225], v[154:155], 0, s[22:23]
	s_mov_b64 s[22:23], 0x30000
	v_lshl_add_u64 v[226:227], v[154:155], 0, s[22:23]
	s_mov_b64 s[22:23], 0x80000
	v_lshl_add_u64 v[240:241], v[154:155], 0, s[22:23]
	s_mov_b64 s[22:23], 0x90000
	v_lshl_add_u64 v[242:243], v[154:155], 0, s[22:23]
	s_mov_b64 s[22:23], 0xa0000
	v_lshl_add_u64 v[244:245], v[154:155], 0, s[22:23]
	s_mov_b64 s[22:23], 0xb0000
	v_lshl_add_u64 v[246:247], v[154:155], 0, s[22:23]
	s_sub_u32 s100, s14, s4
	s_subb_u32 s101, s15, s5
	global_load_dwordx4 v[160:163], v[154:155], off
	global_load_dwordx4 v[164:167], v[154:155], off offset:64
	global_load_dwordx4 v[168:171], v[154:155], off offset:512
	global_load_dwordx4 v[172:175], v[154:155], off offset:576
	global_load_dwordx4 v[176:179], v[196:197], off
	global_load_dwordx4 v[180:183], v[196:197], off offset:64
	global_load_dwordx4 v[184:187], v[196:197], off offset:512
	global_load_dwordx4 v[188:191], v[196:197], off offset:576
	global_load_dwordx4 v[192:195], v[224:225], off
	global_load_dwordx4 v[208:211], v[224:225], off offset:64
	global_load_dwordx4 v[212:215], v[224:225], off offset:512
	global_load_dwordx4 v[216:219], v[224:225], off offset:576
	global_load_dwordx4 v[220:223], v[226:227], off
	global_load_dwordx4 v[138:141], v[226:227], off offset:64
	global_load_dwordx4 v[134:137], v[226:227], off offset:512
	global_load_dwordx4 v[130:133], v[226:227], off offset:576
	s_waitcnt vmcnt(12)
	v_pk_fma_f32 v[126:127], v[126:127], 0.5, v[160:161] op_sel_hi:[1,0,1]
	v_pk_fma_f32 v[128:129], v[128:129], 0.5, v[162:163] op_sel_hi:[1,0,1]
	v_pk_fma_f32 v[122:123], v[122:123], 0.5, v[164:165] op_sel_hi:[1,0,1]
	v_pk_fma_f32 v[124:125], v[124:125], 0.5, v[166:167] op_sel_hi:[1,0,1]
	v_pk_fma_f32 v[114:115], v[114:115], 0.5, v[168:169] op_sel_hi:[1,0,1]
	v_pk_fma_f32 v[116:117], v[116:117], 0.5, v[170:171] op_sel_hi:[1,0,1]
	v_pk_fma_f32 v[110:111], v[110:111], 0.5, v[172:173] op_sel_hi:[1,0,1]
	v_pk_fma_f32 v[112:113], v[112:113], 0.5, v[174:175] op_sel_hi:[1,0,1]
	s_waitcnt vmcnt(8)
	v_pk_fma_f32 v[118:119], v[118:119], 0.5, v[176:177] op_sel_hi:[1,0,1]
	v_pk_fma_f32 v[120:121], v[120:121], 0.5, v[178:179] op_sel_hi:[1,0,1]
	v_pk_fma_f32 v[106:107], v[106:107], 0.5, v[180:181] op_sel_hi:[1,0,1]
	v_pk_fma_f32 v[108:109], v[108:109], 0.5, v[182:183] op_sel_hi:[1,0,1]
	v_pk_fma_f32 v[98:99], v[98:99], 0.5, v[184:185] op_sel_hi:[1,0,1]
	v_pk_fma_f32 v[100:101], v[100:101], 0.5, v[186:187] op_sel_hi:[1,0,1]
	v_pk_fma_f32 v[94:95], v[94:95], 0.5, v[188:189] op_sel_hi:[1,0,1]
	v_pk_fma_f32 v[96:97], v[96:97], 0.5, v[190:191] op_sel_hi:[1,0,1]
	s_waitcnt vmcnt(4)
	v_pk_fma_f32 v[102:103], v[102:103], 0.5, v[192:193] op_sel_hi:[1,0,1]
	v_pk_fma_f32 v[104:105], v[104:105], 0.5, v[194:195] op_sel_hi:[1,0,1]
	v_pk_fma_f32 v[90:91], v[90:91], 0.5, v[208:209] op_sel_hi:[1,0,1]
	v_pk_fma_f32 v[92:93], v[92:93], 0.5, v[210:211] op_sel_hi:[1,0,1]
	v_pk_fma_f32 v[82:83], v[82:83], 0.5, v[212:213] op_sel_hi:[1,0,1]
	v_pk_fma_f32 v[84:85], v[84:85], 0.5, v[214:215] op_sel_hi:[1,0,1]
	v_pk_fma_f32 v[78:79], v[78:79], 0.5, v[216:217] op_sel_hi:[1,0,1]
	v_pk_fma_f32 v[80:81], v[80:81], 0.5, v[218:219] op_sel_hi:[1,0,1]
	s_waitcnt vmcnt(0)
	v_pk_fma_f32 v[86:87], v[86:87], 0.5, v[220:221] op_sel_hi:[1,0,1]
	v_pk_fma_f32 v[88:89], v[88:89], 0.5, v[222:223] op_sel_hi:[1,0,1]
	v_pk_fma_f32 v[74:75], v[74:75], 0.5, v[138:139] op_sel_hi:[1,0,1]
	v_pk_fma_f32 v[76:77], v[76:77], 0.5, v[140:141] op_sel_hi:[1,0,1]
	v_pk_fma_f32 v[70:71], v[70:71], 0.5, v[134:135] op_sel_hi:[1,0,1]
	v_pk_fma_f32 v[72:73], v[72:73], 0.5, v[136:137] op_sel_hi:[1,0,1]
	v_pk_fma_f32 v[66:67], v[66:67], 0.5, v[130:131] op_sel_hi:[1,0,1]
	v_pk_fma_f32 v[68:69], v[68:69], 0.5, v[132:133] op_sel_hi:[1,0,1]
	global_load_dwordx4 v[160:163], v[240:241], off
	global_load_dwordx4 v[164:167], v[240:241], off offset:64
	global_load_dwordx4 v[168:171], v[240:241], off offset:512
	global_load_dwordx4 v[172:175], v[240:241], off offset:576
	global_load_dwordx4 v[176:179], v[242:243], off
	global_load_dwordx4 v[180:183], v[242:243], off offset:64
	global_load_dwordx4 v[184:187], v[242:243], off offset:512
	global_load_dwordx4 v[188:191], v[242:243], off offset:576
	global_load_dwordx4 v[192:195], v[244:245], off
	global_load_dwordx4 v[208:211], v[244:245], off offset:64
	global_load_dwordx4 v[212:215], v[244:245], off offset:512
	global_load_dwordx4 v[216:219], v[244:245], off offset:576
	global_load_dwordx4 v[220:223], v[246:247], off
	global_load_dwordx4 v[138:141], v[246:247], off offset:64
	global_load_dwordx4 v[134:137], v[246:247], off offset:512
	global_load_dwordx4 v[130:133], v[246:247], off offset:576
	v_lshl_add_u64 v[154:155], v[154:155], 0, s[100:101]
	v_lshl_add_u64 v[196:197], v[196:197], 0, s[100:101]
	v_lshl_add_u64 v[224:225], v[224:225], 0, s[100:101]
	v_lshl_add_u64 v[226:227], v[226:227], 0, s[100:101]
	global_store_dwordx4 v[154:155], v[126:129], off
	global_store_dwordx4 v[154:155], v[122:125], off offset:64
	global_store_dwordx4 v[154:155], v[114:117], off offset:512
	global_store_dwordx4 v[154:155], v[110:113], off offset:576
	global_store_dwordx4 v[196:197], v[118:121], off
	global_store_dwordx4 v[196:197], v[106:109], off offset:64
	global_store_dwordx4 v[196:197], v[98:101], off offset:512
	global_store_dwordx4 v[196:197], v[94:97], off offset:576
	global_store_dwordx4 v[224:225], v[102:105], off
	global_store_dwordx4 v[224:225], v[90:93], off offset:64
	global_store_dwordx4 v[224:225], v[82:85], off offset:512
	global_store_dwordx4 v[224:225], v[78:81], off offset:576
	global_store_dwordx4 v[226:227], v[86:89], off
	global_store_dwordx4 v[226:227], v[74:77], off offset:64
	global_store_dwordx4 v[226:227], v[70:73], off offset:512
	global_store_dwordx4 v[226:227], v[66:69], off offset:576
	s_waitcnt vmcnt(0)
	v_pk_fma_f32 v[62:63], v[62:63], 0.5, v[160:161] op_sel_hi:[1,0,1]
	v_pk_fma_f32 v[64:65], v[64:65], 0.5, v[162:163] op_sel_hi:[1,0,1]
	v_pk_fma_f32 v[58:59], v[58:59], 0.5, v[164:165] op_sel_hi:[1,0,1]
	v_pk_fma_f32 v[60:61], v[60:61], 0.5, v[166:167] op_sel_hi:[1,0,1]
	v_pk_fma_f32 v[42:43], v[42:43], 0.5, v[168:169] op_sel_hi:[1,0,1]
	v_pk_fma_f32 v[44:45], v[44:45], 0.5, v[170:171] op_sel_hi:[1,0,1]
	v_pk_fma_f32 v[34:35], v[34:35], 0.5, v[172:173] op_sel_hi:[1,0,1]
	v_pk_fma_f32 v[36:37], v[36:37], 0.5, v[174:175] op_sel_hi:[1,0,1]
	v_pk_fma_f32 v[54:55], v[54:55], 0.5, v[176:177] op_sel_hi:[1,0,1]
	v_pk_fma_f32 v[56:57], v[56:57], 0.5, v[178:179] op_sel_hi:[1,0,1]
	v_pk_fma_f32 v[50:51], v[50:51], 0.5, v[180:181] op_sel_hi:[1,0,1]
	v_pk_fma_f32 v[52:53], v[52:53], 0.5, v[182:183] op_sel_hi:[1,0,1]
	v_pk_fma_f32 v[26:27], v[26:27], 0.5, v[184:185] op_sel_hi:[1,0,1]
	v_pk_fma_f32 v[28:29], v[28:29], 0.5, v[186:187] op_sel_hi:[1,0,1]
	v_pk_fma_f32 v[22:23], v[22:23], 0.5, v[188:189] op_sel_hi:[1,0,1]
	v_pk_fma_f32 v[24:25], v[24:25], 0.5, v[190:191] op_sel_hi:[1,0,1]
	v_pk_fma_f32 v[46:47], v[46:47], 0.5, v[192:193] op_sel_hi:[1,0,1]
	v_pk_fma_f32 v[48:49], v[48:49], 0.5, v[194:195] op_sel_hi:[1,0,1]
	v_pk_fma_f32 v[38:39], v[38:39], 0.5, v[208:209] op_sel_hi:[1,0,1]
	v_pk_fma_f32 v[40:41], v[40:41], 0.5, v[210:211] op_sel_hi:[1,0,1]
	v_pk_fma_f32 v[12:13], v[12:13], 0.5, v[212:213] op_sel_hi:[1,0,1]
	v_pk_fma_f32 v[14:15], v[14:15], 0.5, v[214:215] op_sel_hi:[1,0,1]
	v_pk_fma_f32 v[8:9], v[8:9], 0.5, v[216:217] op_sel_hi:[1,0,1]
	v_pk_fma_f32 v[10:11], v[10:11], 0.5, v[218:219] op_sel_hi:[1,0,1]
	v_pk_fma_f32 v[30:31], v[30:31], 0.5, v[220:221] op_sel_hi:[1,0,1]
	v_pk_fma_f32 v[32:33], v[32:33], 0.5, v[222:223] op_sel_hi:[1,0,1]
	v_pk_fma_f32 v[18:19], v[18:19], 0.5, v[138:139] op_sel_hi:[1,0,1]
	v_pk_fma_f32 v[20:21], v[20:21], 0.5, v[140:141] op_sel_hi:[1,0,1]
	v_pk_fma_f32 v[4:5], v[4:5], 0.5, v[134:135] op_sel_hi:[1,0,1]
	v_pk_fma_f32 v[6:7], v[6:7], 0.5, v[136:137] op_sel_hi:[1,0,1]
	v_pk_fma_f32 v[0:1], v[0:1], 0.5, v[130:131] op_sel_hi:[1,0,1]
	v_pk_fma_f32 v[2:3], v[2:3], 0.5, v[132:133] op_sel_hi:[1,0,1]
	v_lshl_add_u64 v[240:241], v[240:241], 0, s[100:101]
	v_lshl_add_u64 v[242:243], v[242:243], 0, s[100:101]
	v_lshl_add_u64 v[244:245], v[244:245], 0, s[100:101]
	v_lshl_add_u64 v[246:247], v[246:247], 0, s[100:101]
	global_store_dwordx4 v[240:241], v[62:65], off
	global_store_dwordx4 v[240:241], v[58:61], off offset:64
	global_store_dwordx4 v[240:241], v[42:45], off offset:512
	global_store_dwordx4 v[240:241], v[34:37], off offset:576
	global_store_dwordx4 v[242:243], v[54:57], off
	global_store_dwordx4 v[242:243], v[50:53], off offset:64
	global_store_dwordx4 v[242:243], v[26:29], off offset:512
	global_store_dwordx4 v[242:243], v[22:25], off offset:576
	global_store_dwordx4 v[244:245], v[46:49], off
	global_store_dwordx4 v[244:245], v[38:41], off offset:64
	global_store_dwordx4 v[244:245], v[12:15], off offset:512
	global_store_dwordx4 v[244:245], v[8:11], off offset:576
	global_store_dwordx4 v[246:247], v[30:33], off
	global_store_dwordx4 v[246:247], v[18:21], off offset:64
	global_store_dwordx4 v[246:247], v[4:7], off offset:512
	global_store_dwordx4 v[246:247], v[0:3], off offset:576
	s_and_b64 vcc, exec, s[38:39]
	s_mov_b32 s12, s82
	s_mov_b32 s2, s83
	s_mov_b64 s[28:29], s[18:19]
	s_mov_b64 s[22:23], s[16:17]
	s_mov_b32 s86, 0x38c0000
	s_cbranch_vccz .LBB0_122
	s_waitcnt vmcnt(0)
	s_cmpk_gt_u32 s48, 0xff
	s_cbranch_scc1 .LBB0_137
	s_barrier

.LBB0_174:
	s_add_u32 s40, s22, 0x100
	s_addc_u32 s41, s23, 0
	s_add_i32 s83, 0, 0x10000
	v_add_u32_e32 v148, s83, v157
	ds_read_b128 v[130:133], v148
	ds_read_b128 v[134:137], v148 offset:1024
	ds_read_b128 v[138:141], v148 offset:2048
	ds_read_b128 v[148:151], v148 offset:3072
	s_cmp_eq_u32 s82, 12
	s_cselect_b32 s49, s9, s41
	s_cselect_b32 s48, s12, s40
	s_cselect_b32 s43, s5, s79
	s_cselect_b32 s42, s34, s61
	v_lshl_add_u64 v[188:189], s[22:23], 0, v[146:147]
	s_add_i32 m0, s19, 0xc000
	ds_read_b128 v[152:155], v159
	ds_read_b128 v[160:163], v159 offset:1024
	ds_read_b128 v[164:167], v159 offset:2048
	ds_read_b128 v[168:171], v159 offset:3072
	ds_read_b128 v[172:175], v159 offset:4096
	ds_read_b128 v[176:179], v159 offset:5120
	ds_read_b128 v[180:183], v159 offset:6144
	ds_read_b128 v[184:187], v159 offset:7168
	global_load_lds_dwordx4 v[188:189], off
	v_lshl_add_u64 v[188:189], s[22:23], 0, v[144:145]
	s_add_i32 m0, s19, 0xe000
	s_nop 0
	global_load_lds_dwordx4 v[188:189], off
	s_waitcnt lgkmcnt(8)
	s_barrier
	s_waitcnt lgkmcnt(0)
	s_waitcnt lgkmcnt(0)
	v_mfma_f32_16x16x32_bf16 v[126:129], v[130:133], v[152:155], v[126:129]
	v_mfma_f32_16x16x32_bf16 v[122:125], v[138:141], v[152:155], v[122:125]
	v_mfma_f32_16x16x32_bf16 v[118:121], v[130:133], v[164:167], v[118:121]
	v_mfma_f32_16x16x32_bf16 v[106:109], v[138:141], v[164:167], v[106:109]
	v_mfma_f32_16x16x32_bf16 v[102:105], v[130:133], v[172:175], v[102:105]
	v_mfma_f32_16x16x32_bf16 v[90:93], v[138:141], v[172:175], v[90:93]
	v_mfma_f32_16x16x32_bf16 v[86:89], v[130:133], v[180:183], v[86:89]
	v_mfma_f32_16x16x32_bf16 v[74:77], v[138:141], v[180:183], v[74:77]
	v_mfma_f32_16x16x32_bf16 v[126:129], v[134:137], v[160:163], v[126:129]
	v_mfma_f32_16x16x32_bf16 v[122:125], v[148:151], v[160:163], v[122:125]
	v_mfma_f32_16x16x32_bf16 v[118:121], v[134:137], v[168:171], v[118:121]
	v_mfma_f32_16x16x32_bf16 v[106:109], v[148:151], v[168:171], v[106:109]
	v_mfma_f32_16x16x32_bf16 v[102:105], v[134:137], v[176:179], v[102:105]
	v_mfma_f32_16x16x32_bf16 v[90:93], v[148:151], v[176:179], v[90:93]
	v_mfma_f32_16x16x32_bf16 v[86:89], v[134:137], v[184:187], v[86:89]
	v_mfma_f32_16x16x32_bf16 v[74:77], v[148:151], v[184:187], v[74:77]
	s_barrier
	s_add_i32 s84, 0, 0x14000
	v_add_u32_e32 v196, s84, v157
	s_add_i32 s22, s83, s52
	ds_read_b128 v[188:191], v196
	ds_read_b128 v[192:195], v196 offset:1024
	ds_read_b128 v[208:211], v196 offset:2048
	ds_read_b128 v[212:215], v196 offset:3072
	v_lshl_add_u64 v[196:197], s[42:43], 0, v[16:17]
	s_mov_b32 m0, s22
	v_lshl_add_u64 v[216:217], s[42:43], 0, v[142:143]
	global_load_lds_dwordx4 v[196:197], off
	s_add_i32 m0, s22, 0x2000
	s_nop 0
	global_load_lds_dwordx4 v[216:217], off
	s_barrier
	s_waitcnt lgkmcnt(0)
	s_waitcnt lgkmcnt(0)
	v_mfma_f32_16x16x32_bf16 v[114:117], v[188:191], v[152:155], v[114:117]
	v_mfma_f32_16x16x32_bf16 v[110:113], v[208:211], v[152:155], v[110:113]
	v_mfma_f32_16x16x32_bf16 v[98:101], v[188:191], v[164:167], v[98:101]
	v_mfma_f32_16x16x32_bf16 v[94:97], v[208:211], v[164:167], v[94:97]
	v_mfma_f32_16x16x32_bf16 v[82:85], v[188:191], v[172:175], v[82:85]
	v_mfma_f32_16x16x32_bf16 v[78:81], v[208:211], v[172:175], v[78:81]
	v_mfma_f32_16x16x32_bf16 v[70:73], v[188:191], v[180:183], v[70:73]
	v_mfma_f32_16x16x32_bf16 v[66:69], v[208:211], v[180:183], v[66:69]
	v_mfma_f32_16x16x32_bf16 v[114:117], v[192:195], v[160:163], v[114:117]
	v_mfma_f32_16x16x32_bf16 v[110:113], v[212:215], v[160:163], v[110:113]
	v_mfma_f32_16x16x32_bf16 v[98:101], v[192:195], v[168:171], v[98:101]
	v_mfma_f32_16x16x32_bf16 v[94:97], v[212:215], v[168:171], v[94:97]
	v_mfma_f32_16x16x32_bf16 v[82:85], v[192:195], v[176:179], v[82:85]
	v_mfma_f32_16x16x32_bf16 v[78:81], v[212:215], v[176:179], v[78:81]
	v_mfma_f32_16x16x32_bf16 v[70:73], v[192:195], v[184:187], v[70:73]
	v_mfma_f32_16x16x32_bf16 v[66:69], v[212:215], v[184:187], v[66:69]
	s_mov_b32 m0, s19
	v_lshl_add_u64 v[218:219], s[48:49], 0, v[16:17]
	s_barrier
	ds_read_b128 v[152:155], v159 offset:16384
	ds_read_b128 v[160:163], v159 offset:17408
	ds_read_b128 v[164:167], v159 offset:18432
	ds_read_b128 v[168:171], v159 offset:19456
	ds_read_b128 v[172:175], v159 offset:20480
	ds_read_b128 v[176:179], v159 offset:21504
	ds_read_b128 v[180:183], v159 offset:22528
	ds_read_b128 v[184:187], v159 offset:23552
	global_load_lds_dwordx4 v[218:219], off
	v_lshl_add_u64 v[220:221], s[48:49], 0, v[142:143]
	s_mov_b32 m0, s54
	s_nop 0
	global_load_lds_dwordx4 v[220:221], off
	s_barrier
	s_waitcnt lgkmcnt(0)
	s_waitcnt lgkmcnt(0)
	v_mfma_f32_16x16x32_bf16 v[62:65], v[130:133], v[152:155], v[62:65]
	v_mfma_f32_16x16x32_bf16 v[58:61], v[138:141], v[152:155], v[58:61]
	v_mfma_f32_16x16x32_bf16 v[54:57], v[130:133], v[164:167], v[54:57]
	v_mfma_f32_16x16x32_bf16 v[50:53], v[138:141], v[164:167], v[50:53]
	v_mfma_f32_16x16x32_bf16 v[46:49], v[130:133], v[172:175], v[46:49]
	v_mfma_f32_16x16x32_bf16 v[38:41], v[138:141], v[172:175], v[38:41]
	v_mfma_f32_16x16x32_bf16 v[30:33], v[130:133], v[180:183], v[30:33]
	v_mfma_f32_16x16x32_bf16 v[18:21], v[138:141], v[180:183], v[18:21]
	v_mfma_f32_16x16x32_bf16 v[62:65], v[134:137], v[160:163], v[62:65]
	v_mfma_f32_16x16x32_bf16 v[58:61], v[148:151], v[160:163], v[58:61]
	v_mfma_f32_16x16x32_bf16 v[54:57], v[134:137], v[168:171], v[54:57]
	v_mfma_f32_16x16x32_bf16 v[50:53], v[148:151], v[168:171], v[50:53]
	v_mfma_f32_16x16x32_bf16 v[46:49], v[134:137], v[176:179], v[46:49]
	v_mfma_f32_16x16x32_bf16 v[38:41], v[148:151], v[176:179], v[38:41]
	v_mfma_f32_16x16x32_bf16 v[30:33], v[134:137], v[184:187], v[30:33]
	v_mfma_f32_16x16x32_bf16 v[18:21], v[148:151], v[184:187], v[18:21]
	s_barrier
	s_add_u32 s22, s42, 0x40000
	s_addc_u32 s23, s43, 0
	s_add_i32 s83, s84, s52
	v_lshl_add_u64 v[130:131], s[22:23], 0, v[16:17]
	s_mov_b32 m0, s83
	s_nop 0
	global_load_lds_dwordx4 v[130:131], off
	v_lshl_add_u64 v[130:131], s[22:23], 0, v[142:143]
	s_add_i32 m0, s83, 0x2000
	s_nop 0
	global_load_lds_dwordx4 v[130:131], off
	s_waitcnt vmcnt(6)
	s_barrier
	v_mfma_f32_16x16x32_bf16 v[42:45], v[188:191], v[152:155], v[42:45]
	v_mfma_f32_16x16x32_bf16 v[34:37], v[208:211], v[152:155], v[34:37]
	v_mfma_f32_16x16x32_bf16 v[26:29], v[188:191], v[164:167], v[26:29]
	v_mfma_f32_16x16x32_bf16 v[22:25], v[208:211], v[164:167], v[22:25]
	v_mfma_f32_16x16x32_bf16 v[12:15], v[188:191], v[172:175], v[12:15]
	v_mfma_f32_16x16x32_bf16 v[8:11], v[208:211], v[172:175], v[8:11]
	v_mfma_f32_16x16x32_bf16 v[4:7], v[188:191], v[180:183], v[4:7]
	v_mfma_f32_16x16x32_bf16 v[0:3], v[208:211], v[180:183], v[0:3]
	v_mfma_f32_16x16x32_bf16 v[42:45], v[192:195], v[160:163], v[42:45]
	v_mfma_f32_16x16x32_bf16 v[34:37], v[212:215], v[160:163], v[34:37]
	v_mfma_f32_16x16x32_bf16 v[26:29], v[192:195], v[168:171], v[26:29]
	v_mfma_f32_16x16x32_bf16 v[22:25], v[212:215], v[168:171], v[22:25]
	v_mfma_f32_16x16x32_bf16 v[12:15], v[192:195], v[176:179], v[12:15]
	v_mfma_f32_16x16x32_bf16 v[8:11], v[212:215], v[176:179], v[8:11]
	v_mfma_f32_16x16x32_bf16 v[4:7], v[192:195], v[184:187], v[4:7]
	v_mfma_f32_16x16x32_bf16 v[0:3], v[212:215], v[184:187], v[0:3]
	s_add_i32 s83, 0, 0x18000
	v_add_u32_e32 v148, s83, v157
	s_barrier
	ds_read_b128 v[130:133], v148
	ds_read_b128 v[134:137], v148 offset:1024
	ds_read_b128 v[138:141], v148 offset:2048
	ds_read_b128 v[148:151], v148 offset:3072
	s_add_u32 s22, s48, 0x40000
	s_addc_u32 s23, s49, 0
	s_mov_b32 m0, s55
	v_lshl_add_u64 v[188:189], s[22:23], 0, v[16:17]
	ds_read_b128 v[152:155], v159 offset:32768
	ds_read_b128 v[160:163], v159 offset:33792
	ds_read_b128 v[164:167], v159 offset:34816
	ds_read_b128 v[168:171], v159 offset:35840
	ds_read_b128 v[172:175], v159 offset:36864
	ds_read_b128 v[176:179], v159 offset:37888
	ds_read_b128 v[180:183], v159 offset:38912
	ds_read_b128 v[184:187], v159 offset:39936
	global_load_lds_dwordx4 v[188:189], off
	v_lshl_add_u64 v[188:189], s[22:23], 0, v[142:143]
	s_mov_b32 m0, s56
	s_nop 0
	global_load_lds_dwordx4 v[188:189], off
	s_waitcnt lgkmcnt(8)
	s_barrier
	s_waitcnt lgkmcnt(0)
	s_waitcnt lgkmcnt(0)
	v_mfma_f32_16x16x32_bf16 v[126:129], v[130:133], v[152:155], v[126:129]
	v_mfma_f32_16x16x32_bf16 v[122:125], v[138:141], v[152:155], v[122:125]
	v_mfma_f32_16x16x32_bf16 v[118:121], v[130:133], v[164:167], v[118:121]
	v_mfma_f32_16x16x32_bf16 v[106:109], v[138:141], v[164:167], v[106:109]
	v_mfma_f32_16x16x32_bf16 v[102:105], v[130:133], v[172:175], v[102:105]
	v_mfma_f32_16x16x32_bf16 v[90:93], v[138:141], v[172:175], v[90:93]
	v_mfma_f32_16x16x32_bf16 v[86:89], v[130:133], v[180:183], v[86:89]
	v_mfma_f32_16x16x32_bf16 v[74:77], v[138:141], v[180:183], v[74:77]
	v_mfma_f32_16x16x32_bf16 v[126:129], v[134:137], v[160:163], v[126:129]
	v_mfma_f32_16x16x32_bf16 v[122:125], v[148:151], v[160:163], v[122:125]
	v_mfma_f32_16x16x32_bf16 v[118:121], v[134:137], v[168:171], v[118:121]
	v_mfma_f32_16x16x32_bf16 v[106:109], v[148:151], v[168:171], v[106:109]
	v_mfma_f32_16x16x32_bf16 v[102:105], v[134:137], v[176:179], v[102:105]
	v_mfma_f32_16x16x32_bf16 v[90:93], v[148:151], v[176:179], v[90:93]
	v_mfma_f32_16x16x32_bf16 v[86:89], v[134:137], v[184:187], v[86:89]
	v_mfma_f32_16x16x32_bf16 v[74:77], v[148:151], v[184:187], v[74:77]
	s_barrier
	s_add_i32 s48, 0, 0x1c000
	s_add_i32 s22, s83, s52
	v_add_u32_e32 v212, s48, v157
	v_lshl_add_u64 v[196:197], v[196:197], 0, s[10:11]
	s_mov_b32 m0, s22
	ds_read_b128 v[188:191], v212
	ds_read_b128 v[192:195], v212 offset:1024
	ds_read_b128 v[208:211], v212 offset:2048
	ds_read_b128 v[212:215], v212 offset:3072
	global_load_lds_dwordx4 v[196:197], off
	v_lshl_add_u64 v[196:197], v[216:217], 0, s[10:11]
	s_add_i32 m0, s22, 0x2000
	s_nop 0
	global_load_lds_dwordx4 v[196:197], off
	s_barrier
	s_waitcnt lgkmcnt(0)
	s_waitcnt lgkmcnt(0)
	v_mfma_f32_16x16x32_bf16 v[114:117], v[188:191], v[152:155], v[114:117]
	v_mfma_f32_16x16x32_bf16 v[110:113], v[208:211], v[152:155], v[110:113]
	v_mfma_f32_16x16x32_bf16 v[98:101], v[188:191], v[164:167], v[98:101]
	v_mfma_f32_16x16x32_bf16 v[94:97], v[208:211], v[164:167], v[94:97]
	v_mfma_f32_16x16x32_bf16 v[82:85], v[188:191], v[172:175], v[82:85]
	v_mfma_f32_16x16x32_bf16 v[78:81], v[208:211], v[172:175], v[78:81]
	v_mfma_f32_16x16x32_bf16 v[70:73], v[188:191], v[180:183], v[70:73]
	v_mfma_f32_16x16x32_bf16 v[66:69], v[208:211], v[180:183], v[66:69]
	v_mfma_f32_16x16x32_bf16 v[114:117], v[192:195], v[160:163], v[114:117]
	v_mfma_f32_16x16x32_bf16 v[110:113], v[212:215], v[160:163], v[110:113]
	v_mfma_f32_16x16x32_bf16 v[98:101], v[192:195], v[168:171], v[98:101]
	v_mfma_f32_16x16x32_bf16 v[94:97], v[212:215], v[168:171], v[94:97]
	v_mfma_f32_16x16x32_bf16 v[82:85], v[192:195], v[176:179], v[82:85]
	v_mfma_f32_16x16x32_bf16 v[78:81], v[212:215], v[176:179], v[78:81]
	v_mfma_f32_16x16x32_bf16 v[70:73], v[192:195], v[184:187], v[70:73]
	v_mfma_f32_16x16x32_bf16 v[66:69], v[212:215], v[184:187], v[66:69]
	s_mov_b32 m0, s57
	v_lshl_add_u64 v[196:197], v[218:219], 0, s[10:11]
	s_barrier
	ds_read_b128 v[152:155], v159 offset:49152
	ds_read_b128 v[160:163], v159 offset:50176
	ds_read_b128 v[164:167], v159 offset:51200
	ds_read_b128 v[168:171], v159 offset:52224
	ds_read_b128 v[172:175], v159 offset:53248
	ds_read_b128 v[176:179], v159 offset:54272
	ds_read_b128 v[180:183], v159 offset:55296
	ds_read_b128 v[184:187], v159 offset:56320
	global_load_lds_dwordx4 v[196:197], off
	v_lshl_add_u64 v[196:197], v[220:221], 0, s[10:11]
	s_mov_b32 m0, s58
	s_nop 0
	global_load_lds_dwordx4 v[196:197], off
	s_barrier
	s_waitcnt lgkmcnt(0)
	s_waitcnt lgkmcnt(0)
	v_mfma_f32_16x16x32_bf16 v[62:65], v[130:133], v[152:155], v[62:65]
	v_mfma_f32_16x16x32_bf16 v[58:61], v[138:141], v[152:155], v[58:61]
	v_mfma_f32_16x16x32_bf16 v[54:57], v[130:133], v[164:167], v[54:57]
	v_mfma_f32_16x16x32_bf16 v[50:53], v[138:141], v[164:167], v[50:53]
	v_mfma_f32_16x16x32_bf16 v[46:49], v[130:133], v[172:175], v[46:49]
	v_mfma_f32_16x16x32_bf16 v[38:41], v[138:141], v[172:175], v[38:41]
	v_mfma_f32_16x16x32_bf16 v[30:33], v[130:133], v[180:183], v[30:33]
	v_mfma_f32_16x16x32_bf16 v[18:21], v[138:141], v[180:183], v[18:21]
	v_mfma_f32_16x16x32_bf16 v[62:65], v[134:137], v[160:163], v[62:65]
	v_mfma_f32_16x16x32_bf16 v[58:61], v[148:151], v[160:163], v[58:61]
	v_mfma_f32_16x16x32_bf16 v[54:57], v[134:137], v[168:171], v[54:57]
	v_mfma_f32_16x16x32_bf16 v[50:53], v[148:151], v[168:171], v[50:53]
	v_mfma_f32_16x16x32_bf16 v[46:49], v[134:137], v[176:179], v[46:49]
	v_mfma_f32_16x16x32_bf16 v[38:41], v[148:151], v[176:179], v[38:41]
	v_mfma_f32_16x16x32_bf16 v[30:33], v[134:137], v[184:187], v[30:33]
	v_mfma_f32_16x16x32_bf16 v[18:21], v[148:151], v[184:187], v[18:21]
	s_barrier
	s_add_u32 s22, s42, 0x40080
	s_addc_u32 s23, s43, 0
	s_add_i32 s42, s48, s52
	v_lshl_add_u64 v[130:131], s[22:23], 0, v[16:17]
	s_mov_b32 m0, s42
	s_nop 0
	global_load_lds_dwordx4 v[130:131], off
	v_lshl_add_u64 v[130:131], s[22:23], 0, v[142:143]
	s_add_i32 m0, s42, 0x2000
	s_nop 0
	global_load_lds_dwordx4 v[130:131], off
	s_waitcnt vmcnt(6)
	s_barrier
	v_mfma_f32_16x16x32_bf16 v[42:45], v[188:191], v[152:155], v[42:45]
	v_mfma_f32_16x16x32_bf16 v[34:37], v[208:211], v[152:155], v[34:37]
	v_mfma_f32_16x16x32_bf16 v[26:29], v[188:191], v[164:167], v[26:29]
	v_mfma_f32_16x16x32_bf16 v[22:25], v[208:211], v[164:167], v[22:25]
	v_mfma_f32_16x16x32_bf16 v[12:15], v[188:191], v[172:175], v[12:15]
	v_mfma_f32_16x16x32_bf16 v[8:11], v[208:211], v[172:175], v[8:11]
	v_mfma_f32_16x16x32_bf16 v[4:7], v[188:191], v[180:183], v[4:7]
	v_mfma_f32_16x16x32_bf16 v[0:3], v[208:211], v[180:183], v[0:3]
	v_mfma_f32_16x16x32_bf16 v[42:45], v[192:195], v[160:163], v[42:45]
	v_mfma_f32_16x16x32_bf16 v[34:37], v[212:215], v[160:163], v[34:37]
	v_mfma_f32_16x16x32_bf16 v[26:29], v[192:195], v[168:171], v[26:29]
	v_mfma_f32_16x16x32_bf16 v[22:25], v[212:215], v[168:171], v[22:25]
	v_mfma_f32_16x16x32_bf16 v[12:15], v[192:195], v[176:179], v[12:15]
	v_mfma_f32_16x16x32_bf16 v[8:11], v[212:215], v[176:179], v[8:11]
	v_mfma_f32_16x16x32_bf16 v[4:7], v[192:195], v[184:187], v[4:7]
	v_mfma_f32_16x16x32_bf16 v[0:3], v[212:215], v[184:187], v[0:3]
	s_add_i32 s82, s82, 2
	s_add_u32 s61, s61, 0x100
	s_addc_u32 s79, s79, 0
	s_cmp_gt_u32 s82, 13
	s_mov_b64 s[22:23], s[40:41]
	s_barrier
	s_cbranch_scc0 .LBB0_174
	v_lshl_or_b32 v132, s2, 8, v158
	v_lshl_add_u32 v130, s18, 8, v156
	v_ashrrev_i32_e32 v133, 31, v132
	v_lshlrev_b64 v[148:149], 2, v[132:133]
	v_ashrrev_i32_e32 v131, 31, v130
	v_lshlrev_b64 v[152:153], 12, v[130:131]
	v_lshl_add_u64 v[150:151], s[20:21], 0, v[148:149]
	v_lshl_add_u64 v[154:155], v[150:151], 0, v[152:153]
	s_mov_b64 s[22:23], 0x10000
	v_lshl_add_u64 v[196:197], v[154:155], 0, s[22:23]
	s_mov_b64 s[22:23], 0x20000
	v_lshl_add_u64 v[224:225], v[154:155], 0, s[22:23]
	s_mov_b64 s[22:23], 0x30000
	v_lshl_add_u64 v[226:227], v[154:155], 0, s[22:23]
	s_mov_b64 s[22:23], 0x80000
	v_lshl_add_u64 v[240:241], v[154:155], 0, s[22:23]
	s_mov_b64 s[22:23], 0x90000
	v_lshl_add_u64 v[242:243], v[154:155], 0, s[22:23]
	s_mov_b64 s[22:23], 0xa0000
	v_lshl_add_u64 v[244:245], v[154:155], 0, s[22:23]
	s_mov_b64 s[22:23], 0xb0000
	v_lshl_add_u64 v[246:247], v[154:155], 0, s[22:23]
	global_load_dwordx4 v[160:163], v[154:155], off
	global_load_dwordx4 v[164:167], v[154:155], off offset:64
	global_load_dwordx4 v[168:171], v[154:155], off offset:512
	global_load_dwordx4 v[172:175], v[154:155], off offset:576
	global_load_dwordx4 v[176:179], v[196:197], off
	global_load_dwordx4 v[180:183], v[196:197], off offset:64
	global_load_dwordx4 v[184:187], v[196:197], off offset:512
	global_load_dwordx4 v[188:191], v[196:197], off offset:576
	global_load_dwordx4 v[192:195], v[224:225], off
	global_load_dwordx4 v[208:211], v[224:225], off offset:64
	global_load_dwordx4 v[212:215], v[224:225], off offset:512
	global_load_dwordx4 v[216:219], v[224:225], off offset:576
	global_load_dwordx4 v[220:223], v[226:227], off
	global_load_dwordx4 v[138:141], v[226:227], off offset:64
	global_load_dwordx4 v[134:137], v[226:227], off offset:512
	global_load_dwordx4 v[130:133], v[226:227], off offset:576
	s_waitcnt vmcnt(12)
	v_pk_add_f32 v[126:127], v[126:127], v[160:161]
	v_pk_add_f32 v[128:129], v[128:129], v[162:163]
	v_pk_add_f32 v[122:123], v[122:123], v[164:165]
	v_pk_add_f32 v[124:125], v[124:125], v[166:167]
	v_pk_add_f32 v[114:115], v[114:115], v[168:169]
	v_pk_add_f32 v[116:117], v[116:117], v[170:171]
	v_pk_add_f32 v[110:111], v[110:111], v[172:173]
	v_pk_add_f32 v[112:113], v[112:113], v[174:175]
	s_waitcnt vmcnt(8)
	v_pk_add_f32 v[118:119], v[118:119], v[176:177]
	v_pk_add_f32 v[120:121], v[120:121], v[178:179]
	v_pk_add_f32 v[106:107], v[106:107], v[180:181]
	v_pk_add_f32 v[108:109], v[108:109], v[182:183]
	v_pk_add_f32 v[98:99], v[98:99], v[184:185]
	v_pk_add_f32 v[100:101], v[100:101], v[186:187]
	v_pk_add_f32 v[94:95], v[94:95], v[188:189]
	v_pk_add_f32 v[96:97], v[96:97], v[190:191]
	s_waitcnt vmcnt(4)
	v_pk_add_f32 v[102:103], v[102:103], v[192:193]
	v_pk_add_f32 v[104:105], v[104:105], v[194:195]
	v_pk_add_f32 v[90:91], v[90:91], v[208:209]
	v_pk_add_f32 v[92:93], v[92:93], v[210:211]
	v_pk_add_f32 v[82:83], v[82:83], v[212:213]
	v_pk_add_f32 v[84:85], v[84:85], v[214:215]
	v_pk_add_f32 v[78:79], v[78:79], v[216:217]
	v_pk_add_f32 v[80:81], v[80:81], v[218:219]
	s_waitcnt vmcnt(0)
	v_pk_add_f32 v[86:87], v[86:87], v[220:221]
	v_pk_add_f32 v[88:89], v[88:89], v[222:223]
	v_pk_add_f32 v[74:75], v[74:75], v[138:139]
	v_pk_add_f32 v[76:77], v[76:77], v[140:141]
	v_pk_add_f32 v[70:71], v[70:71], v[134:135]
	v_pk_add_f32 v[72:73], v[72:73], v[136:137]
	v_pk_add_f32 v[66:67], v[66:67], v[130:131]
	v_pk_add_f32 v[68:69], v[68:69], v[132:133]
	global_load_dwordx4 v[160:163], v[240:241], off
	global_load_dwordx4 v[164:167], v[240:241], off offset:64
	global_load_dwordx4 v[168:171], v[240:241], off offset:512
	global_load_dwordx4 v[172:175], v[240:241], off offset:576
	global_load_dwordx4 v[176:179], v[242:243], off
	global_load_dwordx4 v[180:183], v[242:243], off offset:64
	global_load_dwordx4 v[184:187], v[242:243], off offset:512
	global_load_dwordx4 v[188:191], v[242:243], off offset:576
	global_load_dwordx4 v[192:195], v[244:245], off
	global_load_dwordx4 v[208:211], v[244:245], off offset:64
	global_load_dwordx4 v[212:215], v[244:245], off offset:512
	global_load_dwordx4 v[216:219], v[244:245], off offset:576
	global_load_dwordx4 v[220:223], v[246:247], off
	global_load_dwordx4 v[138:141], v[246:247], off offset:64
	global_load_dwordx4 v[134:137], v[246:247], off offset:512
	global_load_dwordx4 v[130:133], v[246:247], off offset:576
	global_store_dwordx4 v[154:155], v[126:129], off
	global_store_dwordx4 v[154:155], v[122:125], off offset:64
	global_store_dwordx4 v[154:155], v[114:117], off offset:512
	global_store_dwordx4 v[154:155], v[110:113], off offset:576
	global_store_dwordx4 v[196:197], v[118:121], off
	global_store_dwordx4 v[196:197], v[106:109], off offset:64
	global_store_dwordx4 v[196:197], v[98:101], off offset:512
	global_store_dwordx4 v[196:197], v[94:97], off offset:576
	global_store_dwordx4 v[224:225], v[102:105], off
	global_store_dwordx4 v[224:225], v[90:93], off offset:64
	global_store_dwordx4 v[224:225], v[82:85], off offset:512
	global_store_dwordx4 v[224:225], v[78:81], off offset:576
	global_store_dwordx4 v[226:227], v[86:89], off
	global_store_dwordx4 v[226:227], v[74:77], off offset:64
	global_store_dwordx4 v[226:227], v[70:73], off offset:512
	global_store_dwordx4 v[226:227], v[66:69], off offset:576
	s_waitcnt vmcnt(0)
	v_pk_add_f32 v[62:63], v[62:63], v[160:161]
	v_pk_add_f32 v[64:65], v[64:65], v[162:163]
	v_pk_add_f32 v[58:59], v[58:59], v[164:165]
	v_pk_add_f32 v[60:61], v[60:61], v[166:167]
	v_pk_add_f32 v[42:43], v[42:43], v[168:169]
	v_pk_add_f32 v[44:45], v[44:45], v[170:171]
	v_pk_add_f32 v[34:35], v[34:35], v[172:173]
	v_pk_add_f32 v[36:37], v[36:37], v[174:175]
	v_pk_add_f32 v[54:55], v[54:55], v[176:177]
	v_pk_add_f32 v[56:57], v[56:57], v[178:179]
	v_pk_add_f32 v[50:51], v[50:51], v[180:181]
	v_pk_add_f32 v[52:53], v[52:53], v[182:183]
	v_pk_add_f32 v[26:27], v[26:27], v[184:185]
	v_pk_add_f32 v[28:29], v[28:29], v[186:187]
	v_pk_add_f32 v[22:23], v[22:23], v[188:189]
	v_pk_add_f32 v[24:25], v[24:25], v[190:191]
	v_pk_add_f32 v[46:47], v[46:47], v[192:193]
	v_pk_add_f32 v[48:49], v[48:49], v[194:195]
	v_pk_add_f32 v[38:39], v[38:39], v[208:209]
	v_pk_add_f32 v[40:41], v[40:41], v[210:211]
	v_pk_add_f32 v[12:13], v[12:13], v[212:213]
	v_pk_add_f32 v[14:15], v[14:15], v[214:215]
	v_pk_add_f32 v[8:9], v[8:9], v[216:217]
	v_pk_add_f32 v[10:11], v[10:11], v[218:219]
	v_pk_add_f32 v[30:31], v[30:31], v[220:221]
	v_pk_add_f32 v[32:33], v[32:33], v[222:223]
	v_pk_add_f32 v[18:19], v[18:19], v[138:139]
	v_pk_add_f32 v[20:21], v[20:21], v[140:141]
	v_pk_add_f32 v[4:5], v[4:5], v[134:135]
	v_pk_add_f32 v[6:7], v[6:7], v[136:137]
	v_pk_add_f32 v[0:1], v[0:1], v[130:131]
	v_pk_add_f32 v[2:3], v[2:3], v[132:133]
	global_store_dwordx4 v[240:241], v[62:65], off
	global_store_dwordx4 v[240:241], v[58:61], off offset:64
	global_store_dwordx4 v[240:241], v[42:45], off offset:512
	global_store_dwordx4 v[240:241], v[34:37], off offset:576
	global_store_dwordx4 v[242:243], v[54:57], off
	global_store_dwordx4 v[242:243], v[50:53], off offset:64
	global_store_dwordx4 v[242:243], v[26:29], off offset:512
	global_store_dwordx4 v[242:243], v[22:25], off offset:576
	global_store_dwordx4 v[244:245], v[46:49], off
	global_store_dwordx4 v[244:245], v[38:41], off offset:64
	global_store_dwordx4 v[244:245], v[12:15], off offset:512
	global_store_dwordx4 v[244:245], v[8:11], off offset:576
	global_store_dwordx4 v[246:247], v[30:33], off
	global_store_dwordx4 v[246:247], v[18:21], off offset:64
	global_store_dwordx4 v[246:247], v[4:7], off offset:512
	global_store_dwordx4 v[246:247], v[0:3], off offset:576
	v_readlane_b32 s82, v255, 5
	s_and_b64 vcc, exec, s[38:39]
	s_mov_b32 s2, s4
	s_mov_b32 s18, s8
	s_mov_b64 s[40:41], s[16:17]
	s_mov_b64 s[22:23], s[14:15]
	v_readlane_b32 s83, v255, 6
	s_cbranch_vccz .LBB0_167
	s_waitcnt vmcnt(0)
	s_cmpk_gt_u32 s35, 0xff
	s_cbranch_scc1 .LBB0_178
	s_barrier
